# v58 + RWKV epilogue-operand loads issued a chunk ahead into own registers (v109-v119), counted vmcnt per wave class
# speedup vs baseline: 1.0197x; 1.0010x over previous
; __device__ __forceinline__ void rwkv_chunk_item(const P& p, const Ctx& c, int seg, int w, bool save) {
;     ...
;     auto eload = [&](int ch) { const size_t rr = (size_t)b * SEGT + ch * 16 + et;
;         e_g = *(const u32x2*)(SG + rr * DMIX + ech); e_v = *(const u32x2*)(SV + rr * DMIX + ech); e_z = *(const u32x2*)(P2 + rr * P2W + 512 + ech); e_rkr = BRKR[(rr * 24 + hh) * 4 + 2]; };
.LBB0_888:
	s_and_b64 vcc, exec, s[68:69]
	s_cbranch_vccz .Lrw_noeload
	v_lshl_add_u64 v[112:113], v[36:37], 0, s[12:13]
	v_add_co_u32_e32 v114, vcc, 0xe900000, v112
	s_nop 1
	v_addc_co_u32_e32 v115, vcc, 0, v113, vcc
	v_add_co_u32_e32 v112, vcc, 0xdd00000, v112
	s_nop 1
	v_addc_co_u32_e32 v113, vcc, 0, v113, vcc
	global_load_dwordx2 v[116:117], v[114:115], off
	global_load_dwordx2 v[118:119], v[112:113], off
	v_lshl_add_u64 v[112:113], v[34:35], 0, s[12:13]
	global_load_dwordx2 v[110:111], v[112:113], off
	v_lshl_add_u64 v[112:113], v[32:33], 0, s[12:13]
	global_load_dword v109, v[112:113], off

; #define LAS __attribute__((address_space(3)))
; __device__ __forceinline__ void rwkv_chunk_item(const P& p, const Ctx& c, int seg, int w, bool save) {
;     ...
;     auto lstore = [&](int pb, int tidv) { const int t = tidv >> 5, j0 = (tidv & 31) * 2;
;         LAS bf16_t* EA = (LAS bf16_t*)(OB + pb * OPB + O_EA); LAS bf16_t* EB = (LAS bf16_t*)(OB + pb * OPB + O_EB); LAS bf16_t* EBT = (LAS bf16_t*)(OB + pb * OPB + O_EBT);
;         LAS bf16_t* UV = (LAS bf16_t*)(OB + pb * OPB + O_UV); LAS float* GT = (LAS float*)(OB + pb * OPB + O_GT);
;         *(LAS unsigned*)(EA + t * 72 + j0) = ga; *(LAS unsigned*)(EA + (16 + t) * 72 + j0) = gr;
;         *(LAS unsigned*)(EB + t * 72 + j0) = gb; *(LAS unsigned*)(EB + (16 + t) * 72 + j0) = gk;
;         EBT[j0 * 40 + t] = (bf16_t)(gb & 0xFFFFu); EBT[(j0 + 1) * 40 + t] = (bf16_t)(gb >> 16); EBT[j0 * 40 + 16 + t] = (bf16_t)(gk & 0xFFFFu); EBT[(j0 + 1) * 40 + 16 + t] = (bf16_t)(gk >> 16);
;         UV[j0 * 40 + 16 + t] = (bf16_t)(gv & 0xFFFFu); UV[(j0 + 1) * 40 + 16 + t] = (bf16_t)(gv >> 16); UV[j0 * 40 + t] = 0; UV[(j0 + 1) * 40 + t] = 0;
;         if (tidv < 64) GT[tidv] = gg; };
.Lrw_w3_done:
	ds_write2st64_b32 v48, v71, v76 offset1:9
	ds_write2st64_b32 v48, v74, v75 offset0:18 offset1:27
	v_bfe_u32 v104, v44, 5, 1
	v_cmp_ne_u32_e32 vcc, 0, v104
	v_mov_b32_e32 v105, 0x5040100
	v_mov_b32_e32 v106, 0x7060302
	v_mul_u32_u24_e32 v104, 0x4e, v104
	v_cndmask_b32_e32 v105, v105, v106, vcc
	v_add_u32_e32 v104, v47, v104
	v_mov_b32_e32 v106, v74
	v_mov_b32_e32 v107, v74
	s_nop 1
	v_permlane32_swap_b32_e32 v106, v107
	v_perm_b32 v108, v107, v106, v105
	ds_write_b32 v104, v108 offset:9216
	v_mov_b32_e32 v106, v75
	v_mov_b32_e32 v107, v75
	s_nop 1
	v_permlane32_swap_b32_e32 v106, v107
	v_perm_b32 v108, v107, v106, v105
	ds_write_b32 v104, v108 offset:9248
	v_mov_b32_e32 v106, v79
	v_mov_b32_e32 v107, v79
	s_nop 1
	v_permlane32_swap_b32_e32 v106, v107
	v_perm_b32 v108, v107, v106, v105
	ds_write_b32 v104, v108 offset:14368
	ds_write_b32 v104, v5 offset:14336
	s_and_saveexec_b64 s[78:79], s[2:3]
	v_lshl_add_u32 v47, v44, 2, s89
	ds_write_b32 v47, v27 offset:23296
	s_or_b64 exec, exec, s[78:79]
	s_cmp_gt_u32 s86, 29
	s_cbranch_scc0 .LBB0_932

; __device__ __forceinline__ void rwkv_chunk_item(const P& p, const Ctx& c, int seg, int w, bool save) {
;     ...
;     auto eload = [&](int ch) { const size_t rr = (size_t)b * SEGT + ch * 16 + et;
;         e_g = *(const u32x2*)(SG + rr * DMIX + ech); e_v = *(const u32x2*)(SV + rr * DMIX + ech); e_z = *(const u32x2*)(P2 + rr * P2W + 512 + ech); e_rkr = BRKR[(rr * 24 + hh) * 4 + 2]; };
.Lrw_bot_copy:
	v_mov_b64_e32 v[38:39], v[116:117]
	v_mov_b64_e32 v[40:41], v[118:119]
	v_mov_b64_e32 v[42:43], v[110:111]
	v_mov_b32_e32 v2, v109
	v_mov_b64_e32 v[50:51], v[116:117]
	v_mov_b64_e32 v[48:49], v[118:119]
	v_mov_b64_e32 v[46:47], v[110:111]
	v_mov_b32_e32 v44, v109
